# phase 1 filter items: both LDS staging loops unrolled with all tile and bias loads issued up front (8 serialized round trips per item removed)
# speedup vs baseline: 1.0069x; 1.0061x over previous
.LBB0_1326:
	s_waitcnt lgkmcnt(0)
	s_barrier
	s_movk_i32 s12, 0x104
	s_movk_i32 s13, 0x5ff
	s_lshl_b32 s4, s4, 2
	v_readlane_b32 s6, v252, 8
	v_readlane_b32 s7, v252, 9
	s_add_u32 s4, s6, s4
	s_addc_u32 s5, s7, 0
	s_lshl_b32 s11, s10, 7
	v_mov_b32_e32 v111, v1
	v_add_u32_e32 v112, 0x0, v42
	v_ashrrev_i32_e32 v113, 4, v112
	v_add_u32_e32 v108, s11, v113
	v_ashrrev_i32_e32 v109, 31, v108
	v_lshlrev_b64 v[108:109], 8, v[108:109]
	v_add_u32_e32 v110, 0x0, v46
	v_lshlrev_b32_e32 v110, 2, v110
	v_lshl_add_u64 v[108:109], s[4:5], 0, v[108:109]
	v_and_b32_e32 v110, 0xf0, v110
	v_lshl_add_u64 v[108:109], v[108:109], 0, v[110:111]
	v_mul_lo_u32 v84, v113, s12
	v_add3_u32 v84, 32, v84, v110
	global_load_dwordx4 v[68:71], v[108:109], off
	v_add_u32_e32 v112, 0x200, v42
	v_ashrrev_i32_e32 v113, 4, v112
	v_add_u32_e32 v108, s11, v113
	v_ashrrev_i32_e32 v109, 31, v108
	v_lshlrev_b64 v[108:109], 8, v[108:109]
	v_add_u32_e32 v110, 0x800, v46
	v_lshlrev_b32_e32 v110, 2, v110
	v_lshl_add_u64 v[108:109], s[4:5], 0, v[108:109]
	v_and_b32_e32 v110, 0xf0, v110
	v_lshl_add_u64 v[108:109], v[108:109], 0, v[110:111]
	v_mul_lo_u32 v85, v113, s12
	v_add3_u32 v85, 32, v85, v110
	global_load_dwordx4 v[72:75], v[108:109], off
	v_add_u32_e32 v112, 0x400, v42
	v_ashrrev_i32_e32 v113, 4, v112
	v_add_u32_e32 v108, s11, v113
	v_ashrrev_i32_e32 v109, 31, v108
	v_lshlrev_b64 v[108:109], 8, v[108:109]
	v_add_u32_e32 v110, 0x1000, v46
	v_lshlrev_b32_e32 v110, 2, v110
	v_lshl_add_u64 v[108:109], s[4:5], 0, v[108:109]
	v_and_b32_e32 v110, 0xf0, v110
	v_lshl_add_u64 v[108:109], v[108:109], 0, v[110:111]
	v_mul_lo_u32 v86, v113, s12
	v_add3_u32 v86, 32, v86, v110
	global_load_dwordx4 v[76:79], v[108:109], off
	v_add_u32_e32 v112, 0x600, v42
	v_ashrrev_i32_e32 v113, 4, v112
	v_add_u32_e32 v108, s11, v113
	v_ashrrev_i32_e32 v109, 31, v108
	v_lshlrev_b64 v[108:109], 8, v[108:109]
	v_add_u32_e32 v110, 0x1800, v46
	v_lshlrev_b32_e32 v110, 2, v110
	v_lshl_add_u64 v[108:109], s[4:5], 0, v[108:109]
	v_and_b32_e32 v110, 0xf0, v110
	v_lshl_add_u64 v[108:109], v[108:109], 0, v[110:111]
	v_mul_lo_u32 v87, v113, s12
	v_add3_u32 v87, 32, v87, v110
	global_load_dwordx4 v[80:83], v[108:109], off
	s_lshl_b32 s2, s8, 7
	s_and_b32 s11, s2, 0x780
	s_movk_i32 s12, 0x5ff
	v_readlane_b32 s16, v254, 23
	s_lshl_b32 s4, s11, 2
	v_readlane_b32 s30, v254, 37
	v_readlane_b32 s31, v254, 38
	s_add_u32 s4, s30, s4
	s_addc_u32 s5, s31, 0
	v_readlane_b32 s17, v254, 24
	v_readlane_b32 s18, v254, 25
	v_readlane_b32 s19, v254, 26
	v_readlane_b32 s20, v254, 27
	v_readlane_b32 s21, v254, 28
	v_readlane_b32 s22, v254, 29
	v_readlane_b32 s23, v254, 30
	v_readlane_b32 s24, v254, 31
	v_readlane_b32 s25, v254, 32
	v_readlane_b32 s26, v254, 33
	v_readlane_b32 s27, v254, 34
	v_readlane_b32 s28, v254, 35
	v_readlane_b32 s29, v254, 36
	v_add_u32_e32 v112, 0x0, v42
	v_ashrrev_i32_e32 v113, 5, v112
	v_ashrrev_i32_e32 v109, 31, v113
	v_mov_b32_e32 v108, v113
	v_lshlrev_b64 v[108:109], 13, v[108:109]
	v_add_u32_e32 v110, 0x0, v46
	v_lshlrev_b32_e32 v110, 2, v110
	v_lshl_add_u64 v[108:109], s[4:5], 0, v[108:109]
	v_and_b32_e32 v110, 0x1f0, v110
	v_lshl_add_u64 v[108:109], v[108:109], 0, v[110:111]
	v_lshlrev_b32_e32 v104, 9, v113
	v_add3_u32 v104, 32, v104, v110
	global_load_dwordx4 v[88:91], v[108:109], off
	v_add_u32_e32 v112, 0x200, v42
	v_ashrrev_i32_e32 v113, 5, v112
	v_ashrrev_i32_e32 v109, 31, v113
	v_mov_b32_e32 v108, v113
	v_lshlrev_b64 v[108:109], 13, v[108:109]
	v_add_u32_e32 v110, 0x800, v46
	v_lshlrev_b32_e32 v110, 2, v110
	v_lshl_add_u64 v[108:109], s[4:5], 0, v[108:109]
	v_and_b32_e32 v110, 0x1f0, v110
	v_lshl_add_u64 v[108:109], v[108:109], 0, v[110:111]
	v_lshlrev_b32_e32 v105, 9, v113
	v_add3_u32 v105, 32, v105, v110
	global_load_dwordx4 v[92:95], v[108:109], off
	v_add_u32_e32 v112, 0x400, v42
	v_ashrrev_i32_e32 v113, 5, v112
	v_ashrrev_i32_e32 v109, 31, v113
	v_mov_b32_e32 v108, v113
	v_lshlrev_b64 v[108:109], 13, v[108:109]
	v_add_u32_e32 v110, 0x1000, v46
	v_lshlrev_b32_e32 v110, 2, v110
	v_lshl_add_u64 v[108:109], s[4:5], 0, v[108:109]
	v_and_b32_e32 v110, 0x1f0, v110
	v_lshl_add_u64 v[108:109], v[108:109], 0, v[110:111]
	v_lshlrev_b32_e32 v106, 9, v113
	v_add3_u32 v106, 32, v106, v110
	global_load_dwordx4 v[96:99], v[108:109], off
	v_add_u32_e32 v112, 0x600, v42
	v_ashrrev_i32_e32 v113, 5, v112
	v_ashrrev_i32_e32 v109, 31, v113
	v_mov_b32_e32 v108, v113
	v_lshlrev_b64 v[108:109], 13, v[108:109]
	v_add_u32_e32 v110, 0x1800, v46
	v_lshlrev_b32_e32 v110, 2, v110
	v_lshl_add_u64 v[108:109], s[4:5], 0, v[108:109]
	v_and_b32_e32 v110, 0x1f0, v110
	v_lshl_add_u64 v[108:109], v[108:109], 0, v[110:111]
	v_lshlrev_b32_e32 v107, 9, v113
	v_add3_u32 v107, 32, v107, v110
	global_load_dwordx4 v[100:103], v[108:109], off
	v_add_u32_e32 v10, s11, v44
	v_readlane_b32 s12, v254, 39
	v_ashrrev_i32_e32 v11, 31, v10
	v_readlane_b32 s13, v254, 40
	s_nop 1
	v_lshl_add_u64 v[114:115], v[10:11], 2, s[12:13]
	global_load_dwordx4 v[116:119], v[114:115], off offset:16
	global_load_dwordx4 v[120:123], v[114:115], off
	s_waitcnt vmcnt(9)
	ds_write2_b32 v84, v68, v69 offset1:1
	ds_write2_b32 v84, v70, v71 offset0:2 offset1:3
	s_waitcnt vmcnt(8)
	ds_write2_b32 v85, v72, v73 offset1:1
	ds_write2_b32 v85, v74, v75 offset0:2 offset1:3
	s_waitcnt vmcnt(7)
	ds_write2_b32 v86, v76, v77 offset1:1
	ds_write2_b32 v86, v78, v79 offset0:2 offset1:3
	s_waitcnt vmcnt(6)
	ds_write2_b32 v87, v80, v81 offset1:1
	ds_write2_b32 v87, v82, v83 offset0:2 offset1:3
	s_waitcnt vmcnt(5)
	ds_write_b128 v104, v[88:91] offset:33280
	s_waitcnt vmcnt(4)
	ds_write_b128 v105, v[92:95] offset:33280
	s_waitcnt vmcnt(3)
	ds_write_b128 v106, v[96:99] offset:33280
	s_waitcnt vmcnt(2)
	ds_write_b128 v107, v[100:103] offset:33280
.LBB0_1332:
	v_add_u32_e32 v10, s11, v44
	v_readlane_b32 s12, v254, 39
	v_ashrrev_i32_e32 v11, 31, v10
	v_readlane_b32 s13, v254, 40
	s_waitcnt lgkmcnt(0)
	s_barrier
	v_lshl_add_u64 v[6:7], v[10:11], 2, s[12:13]
	s_waitcnt vmcnt(1)
	v_mov_b32_e32 v2, v116
	v_mov_b32_e32 v3, v117
	v_mov_b32_e32 v4, v118
	v_mov_b32_e32 v5, v119
	s_nop 0
	s_waitcnt vmcnt(0)
	v_mov_b32_e32 v6, v120
	v_mov_b32_e32 v7, v121
	v_mov_b32_e32 v8, v122
	v_mov_b32_e32 v9, v123
	s_mov_b32 s2, 0
	v_mov_b32_e32 v0, v47
	v_readlane_b32 s14, v254, 41
	v_readlane_b32 s15, v254, 42
	v_readlane_b32 s16, v254, 43
	v_readlane_b32 s17, v254, 44
	v_readlane_b32 s18, v254, 45
	v_readlane_b32 s19, v254, 46
	v_readlane_b32 s20, v254, 47
	v_readlane_b32 s21, v254, 48
	v_readlane_b32 s22, v254, 49
	v_readlane_b32 s23, v254, 50
	v_readlane_b32 s24, v254, 51
	v_readlane_b32 s25, v254, 52
	v_readlane_b32 s26, v254, 53
	v_readlane_b32 s27, v254, 54
	s_waitcnt vmcnt(1)
	v_mov_b64_e32 v[14:15], v[4:5]
	v_mov_b64_e32 v[20:21], v[2:3]
	s_waitcnt vmcnt(0)
	v_mov_b64_e32 v[28:29], v[8:9]
	v_mov_b64_e32 v[34:35], v[6:7]
	v_mov_b64_e32 v[16:17], v[4:5]
	v_mov_b64_e32 v[22:23], v[2:3]
	v_mov_b64_e32 v[30:31], v[8:9]
	v_mov_b64_e32 v[36:37], v[6:7]
	v_mov_b64_e32 v[32:33], v[6:7]
	v_mov_b64_e32 v[26:27], v[8:9]
	v_mov_b64_e32 v[18:19], v[2:3]
	v_mov_b64_e32 v[12:13], v[4:5]
